# attention: next K/V tile global loads issued before the step barrier (conditional on not last step) instead of after it
# speedup vs baseline: 1.0207x; 1.0074x over previous
; #define LAS __attribute__((address_space(3)))
; DI void attn_prompt_item(const __attribute__((address_space(4))) Args& a, LAS unsigned char* lds, int ws_, int b, int h, int qt, float lam, bool dry = false) {
;     ...
;     const int tid = tid_now(ws_);
;     const int wave = ws_, lane = tid & 63, qs = wave >> 1, map = wave & 1;
;     const bf16* Qb = (const bf16*)(a.ws + WS_QB); const bf16* Kg = (const bf16*)(a.ws + WS_KB); const bf16* Vg = (const bf16*)(a.ws + WS_VT);
;     const int rb = b * 8192, q0 = qt * 128;
;     const int qrow = rb + q0 + qs * 32 + (lane & 31);
;     bf16x8 Q[4];
; #pragma unroll
;     for (int ds = 0; ds < 4; ++ds) Q[ds] = *(const bf16x8*)(Qb + (size_t)qrow * 1024 + h * 128 + map * 64 + ds * 16 + (lane >> 5) * 8);
;     f32x16 O[4];
; #pragma unroll
;     for (int dt = 0; dt < 4; ++dt)
; #pragma unroll
;         for (int i = 0; i < 16; ++i) O[dt][i] = 0.f;
;     float m = -1e30f, l = 0.f;
;     const int nt = 2 * qt + 2, my_nt = qs < 2 ? nt - 1 : nt;
;     const bf16* ksrc[2]; const bf16* vsrc[2]; int kdst[2], vdst[2];
; #pragma unroll
;     for (int i = 0; i < 2; ++i) {
;         const int id = tid + 512 * i;
;         ksrc[i] = Kg + (size_t)(rb + (id >> 4)) * 1024 + h * 128 + (id & 15) * 8; kdst[i] = (id >> 4) * 272 + (id & 15) * 16;
;         vsrc[i] = Vg + ((size_t)(b * 8 + h) * 128 + (id >> 3)) * 8192 + (id & 7) * 8; vdst[i] = KT_BYTES + (id >> 3) * 144 + (id & 7) * 16;
;     }
;     v4u kx[2], vx[2];
; #pragma unroll
;     for (int i = 0; i < 2; ++i) { kx[i] = *(const v4u*)(ksrc[i]); vx[i] = *(const v4u*)(vsrc[i]); }
; #pragma unroll
;     for (int i = 0; i < 2; ++i) { *(LAS v4u*)(lds + kdst[i]) = kx[i]; *(LAS v4u*)(lds + vdst[i]) = vx[i]; }
;     __syncthreads();
;     ...
;         if (tid == 0) *(LAS unsigned*)(lds + LDS_WQ) = atomicAdd(ctr, 1u);
;         __syncthreads();
;         int item = (int)*(LAS unsigned*)(lds + LDS_WQ);
;         __syncthreads();
;         if (item >= NITEMS) break;
;         if (item < N_SCP) { if (mode & 1) scan_item(a, lds, ws_, true, item >> 5, (item >> 1) & 15, item & 1, dry); continue; }
;         item -= N_SCP;
;         if (item < N_SCS) { if (mode & 1) scan_item(a, lds, ws_, false, item >> 5, (item >> 1) & 15, item & 1, dry); continue; }
;         item -= N_SCS;
;         if (item < N_ATS) { if (mode & 2) attn_sample_item(a, lds, ws_, item >> 3, item & 7, lam, dry); continue; }
;         item -= N_ATS;
.LBB0_1426:
	s_or_b64 exec, exec, s[4:5]
	s_waitcnt lgkmcnt(0)
	s_barrier
	ds_read_b32 v0, v150
	s_movk_i32 s4, 0xaff
	s_waitcnt lgkmcnt(0)
	s_barrier
	v_cmp_lt_i32_e32 vcc, s4, v0
	v_readfirstlane_b32 s93, v0
	s_mov_b64 s[4:5], -1
	s_cbranch_vccnz .LBB0_1421
	s_cmpk_gt_i32 s93, 0x7f
	s_cbranch_scc0 .LBB0_1510
	s_cmpk_gt_u32 s93, 0x27f
	s_cbranch_scc0 .LBB0_1470
	s_cmpk_gt_u32 s93, 0x2ff
	s_cbranch_scc0 .LBB0_1445
	s_add_i32 s4, s93, 0xfffffd00
	s_lshr_b32 s34, s4, 5
	s_bfe_u32 s35, s93, 0x20003
	s_sub_i32 s7, 63, s34
	s_lshl_b32 s9, s35, 13
	s_lshl_b32 s6, s7, 7
	s_add_i32 s8, s9, s87
	s_add_i32 s8, s8, s6
	s_lshl_b32 s6, s93, 7
	s_load_dwordx2 s[4:5], s[20:21], 0x70
	v_mbcnt_lo_u32_b32 v151, -1, 0
	v_mbcnt_hi_u32_b32 v151, -1, v151
	s_and_b32 s6, s6, 0x380
	v_add_u32_e32 v8, s76, v151
	v_and_b32_e32 v23, 31, v151
	s_lshl_b32 s7, s7, 1
	v_or_b32_e32 v96, s8, v23
	s_lshl_b32 s24, s6, 1
	s_lshl_b32 s8, s88, 1
	s_add_i32 s70, s7, 2
	s_or_b32 s7, s7, 1
	v_add_u32_e32 v10, 0x200, v8
	v_lshlrev_b64 v[0:1], 11, v[96:97]
	s_add_u32 s10, s85, s24
	v_lshlrev_b32_e32 v2, 4, v151
	v_ashrrev_i32_e32 v22, 4, v8
	v_ashrrev_i32_e32 v28, 4, v10
	v_lshl_add_u64 v[0:1], s[38:39], 0, v[0:1]
	s_addc_u32 s11, s86, 0
	v_and_b32_e32 v18, 0xf0, v2
	v_mov_b32_e32 v19, v97
	v_add_u32_e32 v4, s9, v22
	v_ashrrev_i32_e32 v24, 3, v8
	v_add_u32_e32 v8, s9, v28
	v_lshl_add_u64 v[16:17], v[0:1], 0, s[24:25]
	v_lshl_add_u64 v[0:1], s[10:11], 0, v[18:19]
	s_lshl_b32 s10, s35, 10
	v_ashrrev_i32_e32 v5, 31, v4
	v_ashrrev_i32_e32 v9, 31, v8
	v_ashrrev_i32_e32 v30, 3, v10
	s_or_b32 s24, s10, s6
	v_lshlrev_b64 v[4:5], 11, v[4:5]
	v_ashrrev_i32_e32 v25, 31, v24
	v_lshlrev_b64 v[8:9], 11, v[8:9]
	v_ashrrev_i32_e32 v31, 31, v30
	v_and_b32_e32 v20, 0x70, v2
	v_mov_b32_e32 v21, v97
	v_lshl_add_u64 v[4:5], v[0:1], 0, v[4:5]
	v_lshl_add_u64 v[6:7], v[24:25], 0, s[24:25]
	v_lshl_add_u64 v[8:9], v[0:1], 0, v[8:9]
	v_lshl_add_u64 v[0:1], v[30:31], 0, s[24:25]
	v_lshl_add_u64 v[2:3], s[40:41], 0, v[20:21]
	v_lshlrev_b64 v[26:27], 14, v[6:7]
	v_lshlrev_b64 v[32:33], 14, v[0:1]
	v_lshl_add_u64 v[6:7], v[2:3], 0, v[26:27]
	v_lshl_add_u64 v[12:13], v[2:3], 0, v[32:33]
	global_load_dwordx4 v[0:3], v[4:5], off
	s_nop 0
	global_load_dwordx4 v[4:7], v[6:7], off
	s_nop 0
	global_load_dwordx4 v[8:11], v[8:9], off
	s_nop 0
	global_load_dwordx4 v[12:15], v[12:13], off
	s_mov_b32 s9, s25
	v_lshrrev_b32_e32 v19, 1, v151
	v_lshl_add_u64 v[16:17], v[16:17], 0, s[8:9]
	v_and_b32_e32 v130, 16, v19
	v_mov_b32_e32 v131, v97
	v_lshl_add_u64 v[16:17], v[16:17], 0, v[130:131]
	global_load_dwordx4 v[110:113], v[16:17], off
	global_load_dwordx4 v[106:109], v[16:17], off offset:32
	global_load_dwordx4 v[102:105], v[16:17], off offset:64
	global_load_dwordx4 v[98:101], v[16:17], off offset:96
	v_mad_u64_u32 v[132:133], s[8:9], v22, s77, v[18:19]
	v_mad_u64_u32 v[134:135], s[8:9], v24, s78, v[20:21]
	v_mad_u64_u32 v[136:137], s[8:9], v28, s77, v[18:19]
	v_mad_u64_u32 v[138:139], s[8:9], v30, s78, v[20:21]
	s_and_b64 s[8:9], s[42:43], exec
	s_cselect_b32 s7, s7, s70
	s_lshl_b32 s8, s34, 1
	v_and_b32_e32 v131, 63, v151
	v_add_u32_e32 v17, 0, v132
	s_sub_i32 s8, 0x7f, s8
	s_lshl_b32 s9, s35, 24
	v_add_u32_e32 v19, 0, v134
	v_add_u32_e32 v21, 0, v136
	v_add_u32_e32 v24, 0, v138
	s_add_u32 s10, s9, 0x1f121000
	v_ashrrev_i32_e32 v29, 31, v28
	v_mul_u32_u24_e32 v153, 0x110, v23
	v_mul_u32_u24_e32 v139, 0x90, v23
	s_addc_u32 s11, 0, 0
	v_ashrrev_i32_e32 v23, 31, v22
	s_lshl_b32 s9, s93, 8
	v_or_b32_e32 v16, 32, v131
	v_or_b32_e32 v32, v32, v20
	v_or_b32_e32 v26, v26, v20
	s_and_b32 s9, s9, 0x700
	v_mov_b32_e32 v48, v97
	v_mov_b32_e32 v49, v97
	s_waitcnt vmcnt(7)
	ds_write_b128 v17, v[0:3]
	s_waitcnt vmcnt(6)
	ds_write_b128 v19, v[4:7] offset:17408
	s_waitcnt vmcnt(5)
	ds_write_b128 v21, v[8:11]
	s_waitcnt vmcnt(4)
	ds_write_b128 v24, v[12:15] offset:17408
	v_or_b32_e32 v0, 0x60, v131
	v_mul_u32_u24_e32 v135, 0x90, v0
	v_lshlrev_b64 v[0:1], 11, v[28:29]
	v_lshl_add_u64 v[144:145], s[10:11], 0, v[0:1]
	v_lshlrev_b64 v[0:1], 11, v[22:23]
	v_lshl_add_u64 v[146:147], s[10:11], 0, v[0:1]
	v_mul_u32_u24_e32 v154, 0x110, v16
	v_mul_u32_u24_e32 v137, 0x90, v16
	v_lshl_add_u64 v[140:141], v[32:33], 0, s[26:27]
	v_lshl_add_u64 v[142:143], v[26:27], 0, s[26:27]
	v_or3_b32 v144, v144, s9, v18
	v_or3_b32 v146, v146, s9, v18
	v_mov_b32_e32 v50, v97
	v_mov_b32_e32 v51, v97
	v_mov_b32_e32 v52, v97
	v_mov_b32_e32 v53, v97
	v_mov_b32_e32 v54, v97
	v_mov_b32_e32 v55, v97
	v_mov_b32_e32 v56, v97
	v_mov_b32_e32 v57, v97
	v_mov_b32_e32 v58, v97
	v_mov_b32_e32 v59, v97
	v_mov_b32_e32 v60, v97
	v_mov_b32_e32 v61, v97
	v_mov_b32_e32 v62, v97
	v_mov_b32_e32 v63, v97
	v_mov_b64_e32 v[32:33], v[48:49]
	v_mov_b64_e32 v[16:17], v[48:49]
	v_mov_b64_e32 v[0:1], v[48:49]
	s_mov_b32 s9, 0
	v_mov_b32_e32 v152, 0xff800000
	v_mov_b32_e32 v209, 0xff800000
	v_mov_b32_e32 v192, 0
	v_mov_b32_e32 v193, 0
	v_mov_b32_e32 v194, 0
	v_mov_b32_e32 v195, 0
	v_mov_b32_e32 v196, 0
	v_mov_b32_e32 v197, 0
	v_mov_b32_e32 v198, 0
	v_mov_b32_e32 v199, 0
	v_mov_b32_e32 v200, 0
	v_mov_b32_e32 v201, 0
	v_mov_b32_e32 v202, 0
	v_mov_b32_e32 v203, 0
	v_mov_b32_e32 v204, 0
	v_mov_b32_e32 v205, 0
	v_mov_b32_e32 v206, 0
	v_mov_b32_e32 v207, 0
	v_mov_b32_e32 v133, 0
	v_mov_b64_e32 v[34:35], v[50:51]
	v_mov_b64_e32 v[36:37], v[52:53]
	v_mov_b64_e32 v[38:39], v[54:55]
	v_mov_b64_e32 v[40:41], v[56:57]
	v_mov_b64_e32 v[42:43], v[58:59]
	v_mov_b64_e32 v[44:45], v[60:61]
	v_mov_b64_e32 v[46:47], v[62:63]
	v_mov_b64_e32 v[18:19], v[50:51]
	v_mov_b64_e32 v[20:21], v[52:53]
	v_mov_b64_e32 v[22:23], v[54:55]
	v_mov_b64_e32 v[24:25], v[56:57]
	v_mov_b64_e32 v[26:27], v[58:59]
	v_mov_b64_e32 v[28:29], v[60:61]
	v_mov_b64_e32 v[30:31], v[62:63]
	v_mov_b64_e32 v[2:3], v[50:51]
	v_mov_b64_e32 v[4:5], v[52:53]
	v_mov_b64_e32 v[6:7], v[54:55]
	v_mov_b64_e32 v[8:9], v[56:57]
	v_mov_b64_e32 v[10:11], v[58:59]
	v_mov_b64_e32 v[12:13], v[60:61]
	v_mov_b64_e32 v[14:15], v[62:63]
	v_lshl_add_u64 v[232:233], s[36:37], 0, v[146:147]
	v_lshl_add_u64 v[234:235], s[36:37], 0, v[142:143]
	global_load_dwordx4 v[118:121], v[232:233], off
	global_load_dwordx4 v[114:117], v[234:235], off
	v_lshl_add_u64 v[232:233], s[36:37], 0, v[144:145]
	v_lshl_add_u64 v[234:235], s[36:37], 0, v[140:141]
	global_load_dwordx4 v[126:129], v[232:233], off
	global_load_dwordx4 v[122:125], v[234:235], off
	s_waitcnt lgkmcnt(0)
	s_barrier
	s_branch .LBB0_1433
; #define LAS __attribute__((address_space(3)))
; DI unsigned pk2(float lo, float hi) { f32x2 v = {lo, hi}; bf16x2_t b = __builtin_convertvector(v, bf16x2_t); return __builtin_bit_cast(unsigned, b); }
; #define MFMA32(a, b, c) __builtin_amdgcn_mfma_f32_32x32x16_bf16((a), (b), (c), 0, 0, 0)
; template <int NK32>
; DI void attn_tile(const LAS unsigned char* Kb, const LAS unsigned char* Vb, int map, int lane, const bf16x8 (&Q)[4], f32x16 (&O)[4], float& m, float& l) {
;     ...
;     float ps = 0.f;
; #pragma unroll
;     for (int kt = 0; kt < NK32; ++kt)
; #pragma unroll
;         for (int i = 0; i < 16; ++i) { const float p = __builtin_amdgcn_exp2f(S[kt][i] - m); S[kt][i] = p; ps += p; }
;     l += ps;
; #pragma unroll
;     for (int sl = 0; sl < 2 * NK32; ++sl) {
;         const int kt = sl >> 1, r0 = 8 * (sl & 1);
;         v4u pu; pu.x = pk2(S[kt][r0 + 0], S[kt][r0 + 1]); pu.y = pk2(S[kt][r0 + 2], S[kt][r0 + 3]); pu.z = pk2(S[kt][r0 + 4], S[kt][r0 + 5]); pu.w = pk2(S[kt][r0 + 6], S[kt][r0 + 7]);
;         const bf16x8 pf = __builtin_bit_cast(bf16x8, pu);
; #pragma unroll
;         for (int dt = 0; dt < 4; ++dt) {
;             const bf16x8 vf = *(const LAS bf16x8*)(Vb + (dt * 32 + r32) * 144 + sl * 32 + hf * 16);
;             O[dt] = MFMA32(vf, pf, O[dt]);
;         }
;     }
; DI void attn_prompt_item(const __attribute__((address_space(4))) Args& a, LAS unsigned char* lds, int ws_, int b, int h, int qt, float lam, bool dry = false) {
;     ...
;     for (int kt = 0; kt < nt; ++kt) {
;         const bool more = kt + 1 < nt;
;         if (more) {
; #pragma unroll
;             for (int i = 0; i < 2; ++i) { kx[i] = *(const v4u*)(ksrc[i] + (size_t)(kt + 1) * 64 * 1024); vx[i] = *(const v4u*)(vsrc[i] + (kt + 1) * 64); }
;         }
;         const LAS unsigned char* buf = lds + (kt & 1) * KV_BYTES;
;         if (kt < my_nt) attn_tile<2>(buf, buf + KT_BYTES, map, lane, Q, O, m, l);
;         if (more) {
;             LAS unsigned char* nb = lds + ((kt + 1) & 1) * KV_BYTES;
; #pragma unroll
;             for (int i = 0; i < 2; ++i) { *(LAS v4u*)(nb + kdst[i]) = kx[i]; *(LAS v4u*)(nb + vdst[i]) = vx[i]; }
;         }
;         __syncthreads();
.LBB0_1431:
	s_sub_i32 s11, 0x8c00, s10
	v_add_u32_e32 v210, s11, v132
	v_add_u32_e32 v211, s11, v134
	v_add_u32_e32 v212, s11, v136
	v_add_u32_e32 v213, s11, v138
	v_exp_f32_e32 v155, v80
	v_exp_f32_e32 v156, v81
	v_exp_f32_e32 v165, v82
	v_exp_f32_e32 v166, v83
	v_exp_f32_e32 v168, v84
	v_add_u32_e32 v174, s10, v130
	v_add_f32_e32 v81, 0, v155
	v_exp_f32_e32 v169, v85
	v_add_u32_e32 v175, v174, v139
	v_add_f32_e32 v164, v156, v81
	v_exp_f32_e32 v173, v86
	ds_read_b128 v[80:83], v175 offset:17408
	v_exp_f32_e32 v176, v87
	v_cvt_pk_bf16_f32 v84, v155, v156
	v_add_u32_e32 v155, v174, v137
	ds_read_b128 v[160:163], v155 offset:17408
	v_cvt_pk_bf16_f32 v85, v165, v166
	v_cvt_pk_bf16_f32 v86, v168, v169
	v_cvt_pk_bf16_f32 v87, v173, v176
	ds_read_b128 v[156:159], v175 offset:17440
	v_add_u32_e32 v174, v174, v135
	s_waitcnt lgkmcnt(2)
	v_mfma_f32_32x32x16_bf16 v[48:63], v[80:83], v[84:87], v[48:63]
	v_add_f32_e32 v80, v165, v164
	v_add_f32_e32 v177, v166, v80
	v_exp_f32_e32 v178, v88
	ds_read_b128 v[80:83], v155 offset:17440
	ds_read_b128 v[164:167], v175 offset:26624
	v_exp_f32_e32 v179, v89
	s_waitcnt lgkmcnt(3)
	v_mfma_f32_32x32x16_bf16 v[32:47], v[160:163], v[84:87], v[32:47]
	v_exp_f32_e32 v180, v90
	v_exp_f32_e32 v181, v91
	ds_read_b128 v[88:91], v174 offset:17408
	ds_read_b128 v[160:163], v175 offset:26656
	s_waitcnt lgkmcnt(2)
	v_mfma_f32_32x32x16_bf16 v[16:31], v[164:167], v[84:87], v[16:31]
	v_exp_f32_e32 v92, v92
	v_exp_f32_e32 v93, v93
	v_exp_f32_e32 v94, v94
	ds_read_b128 v[164:167], v174 offset:17440
	s_waitcnt lgkmcnt(2)
	v_mfma_f32_32x32x16_bf16 v[0:15], v[88:91], v[84:87], v[0:15]
	s_waitcnt vmcnt(3)
	ds_write_b128 v210, v[118:121]
	v_exp_f32_e32 v95, v95
	v_cvt_pk_bf16_f32 v84, v178, v179
	v_cvt_pk_bf16_f32 v85, v180, v181
	v_cvt_pk_bf16_f32 v86, v92, v93
	v_cvt_pk_bf16_f32 v87, v94, v95
	v_add_f32_e32 v88, v168, v177
	v_add_f32_e32 v88, v169, v88
	v_mfma_f32_32x32x16_bf16 v[48:63], v[156:159], v[84:87], v[48:63]
	v_exp_f32_e32 v156, v64
	v_exp_f32_e32 v157, v65
	v_exp_f32_e32 v158, v66
	v_exp_f32_e32 v159, v67
	s_waitcnt lgkmcnt(1)
	v_mfma_f32_32x32x16_bf16 v[16:31], v[160:163], v[84:87], v[16:31]
	v_exp_f32_e32 v160, v68
	v_exp_f32_e32 v161, v69
	v_exp_f32_e32 v162, v70
	ds_read_b128 v[64:67], v175 offset:17472
	v_exp_f32_e32 v163, v71
	v_mfma_f32_32x32x16_bf16 v[32:47], v[80:83], v[84:87], v[32:47]
	s_waitcnt vmcnt(2)
	ds_write_b128 v211, v[114:117] offset:17408
	v_add_f32_e32 v88, v173, v88
	v_add_f32_e32 v88, v176, v88
	v_add_f32_e32 v88, v178, v88
	v_cvt_pk_bf16_f32 v68, v156, v157
	v_cvt_pk_bf16_f32 v69, v158, v159
	v_cvt_pk_bf16_f32 v70, v160, v161
	v_cvt_pk_bf16_f32 v71, v162, v163
	s_waitcnt lgkmcnt(1)
	v_mfma_f32_32x32x16_bf16 v[0:15], v[164:167], v[84:87], v[0:15]
	ds_read_b128 v[80:83], v155 offset:17472
	ds_read_b128 v[84:87], v175 offset:17504
	v_exp_f32_e32 v167, v75
	s_waitcnt lgkmcnt(2)
	v_mfma_f32_32x32x16_bf16 v[48:63], v[64:67], v[68:71], v[48:63]
	v_add_f32_e32 v64, v179, v88
	v_add_f32_e32 v64, v180, v64
	v_add_f32_e32 v164, v181, v64
	v_exp_f32_e32 v165, v72
	ds_read_b128 v[64:67], v175 offset:26688
	ds_read_b128 v[88:91], v155 offset:17504
	v_exp_f32_e32 v155, v73
	s_waitcnt lgkmcnt(3)
	v_mfma_f32_32x32x16_bf16 v[32:47], v[80:83], v[68:71], v[32:47]
	s_waitcnt vmcnt(1)
	ds_write_b128 v212, v[126:129]
	v_exp_f32_e32 v166, v74
	ds_read_b128 v[72:75], v174 offset:17472
	ds_read_b128 v[80:83], v175 offset:26720
	s_waitcnt lgkmcnt(1)
	v_mfma_f32_32x32x16_bf16 v[0:15], v[72:75], v[68:71], v[0:15]
	v_add_f32_e32 v74, v92, v164
	v_add_f32_e32 v74, v93, v74
	v_add_f32_e32 v74, v94, v74
	v_add_f32_e32 v74, v95, v74
	v_add_f32_e32 v74, v156, v74
	v_add_f32_e32 v74, v157, v74
	v_add_f32_e32 v74, v158, v74
	v_mfma_f32_32x32x16_bf16 v[16:31], v[64:67], v[68:71], v[16:31]
	v_exp_f32_e32 v76, v76
	v_exp_f32_e32 v77, v77
	ds_read_b128 v[64:67], v174 offset:17504
	v_add_f32_e32 v74, v159, v74
	v_exp_f32_e32 v72, v78
	v_exp_f32_e32 v73, v79
	v_add_f32_e32 v74, v160, v74
	v_add_f32_e32 v74, v161, v74
	v_add_f32_e32 v74, v162, v74
	v_add_f32_e32 v74, v163, v74
	v_cvt_pk_bf16_f32 v68, v165, v155
	v_cvt_pk_bf16_f32 v69, v166, v167
	v_cvt_pk_bf16_f32 v70, v76, v77
	v_cvt_pk_bf16_f32 v71, v72, v73
	v_add_f32_e32 v74, v165, v74
	v_add_f32_e32 v74, v155, v74
	v_mfma_f32_32x32x16_bf16 v[48:63], v[84:87], v[68:71], v[48:63]
	s_waitcnt vmcnt(0)
	ds_write_b128 v213, v[122:125] offset:17408
	v_add_f32_e32 v74, v166, v74
	v_add_f32_e32 v74, v167, v74
	v_add_f32_e32 v74, v76, v74
	v_add_f32_e32 v74, v77, v74
	v_add_f32_e32 v72, v72, v74
	v_add_f32_e32 v72, v73, v72
	v_add_f32_e32 v133, v133, v72
	v_mfma_f32_32x32x16_bf16 v[32:47], v[88:91], v[68:71], v[32:47]
	s_waitcnt lgkmcnt(1)
	v_mfma_f32_32x32x16_bf16 v[16:31], v[80:83], v[68:71], v[16:31]
	s_waitcnt lgkmcnt(0)
	v_mfma_f32_32x32x16_bf16 v[0:15], v[64:67], v[68:71], v[0:15]
	s_add_i32 s9, s9, 1
	s_bitcmp1_b32 s9, 0
	s_cselect_b32 s10, 0x8c00, 0
	v_lshl_add_u64 v[140:141], v[140:141], 0, s[28:29]
	v_lshl_add_u64 v[142:143], v[142:143], 0, s[28:29]
	v_lshl_add_u64 v[144:145], v[144:145], 0, s[30:31]
	s_cmp_eq_u32 s8, s9
	v_lshl_add_u64 v[146:147], v[146:147], 0, s[30:31]
	s_cbranch_scc1 .Lnold_a
	v_lshl_add_u64 v[228:229], s[36:37], 0, v[146:147]
	v_lshl_add_u64 v[230:231], s[36:37], 0, v[142:143]
	global_load_dwordx4 v[118:121], v[228:229], off
	global_load_dwordx4 v[114:117], v[230:231], off
	v_lshl_add_u64 v[228:229], s[36:37], 0, v[144:145]
	v_lshl_add_u64 v[230:231], s[36:37], 0, v[140:141]
	global_load_dwordx4 v[126:129], v[228:229], off
	global_load_dwordx4 v[122:125], v[230:231], off
.Lnold_a:
	s_waitcnt lgkmcnt(0)
	s_barrier
	s_cbranch_scc1 .LBB0_1436
	s_branch .LBB0_1433
; #define LAS __attribute__((address_space(3)))
; DI float half_max(float v) { auto rr = __builtin_amdgcn_permlane32_swap(__float_as_uint(v), __float_as_uint(v), false, false); return fmaxf(__uint_as_float(rr[0]), __uint_as_float(rr[1])); }
; #define MFMA32(a, b, c) __builtin_amdgcn_mfma_f32_32x32x16_bf16((a), (b), (c), 0, 0, 0)
; template <int NK32>
; DI void attn_tile(const LAS unsigned char* Kb, const LAS unsigned char* Vb, int map, int lane, const bf16x8 (&Q)[4], f32x16 (&O)[4], float& m, float& l) {
;     ...
;     __builtin_amdgcn_s_setprio(1);
; #pragma unroll
;     for (int kt = 0; kt < NK32; ++kt) {
; #pragma unroll
;         for (int i = 0; i < 16; ++i) S[kt][i] = 0.f;
; #pragma unroll
;         for (int ds = 0; ds < 4; ++ds) {
;             const bf16x8 kf = *(const LAS bf16x8*)(Kb + (kt * 32 + r32) * 272 + map * 128 + ds * 32 + hf * 16);
;             S[kt] = MFMA32(kf, Q[ds], S[kt]);
;         }
;     }
;     __builtin_amdgcn_s_setprio(0);
;     float mx = fmaxf(S[0][0], S[0][1]);
; #pragma unroll
;     for (int kt = 0; kt < NK32; ++kt)
; #pragma unroll
;         for (int i = (kt == 0 ? 2 : 0); i < 16; i += 2) mx = fmaxf(fmaxf(mx, S[kt][i]), S[kt][i + 1]);
;     mx = half_max(mx);
;     if (__any(mx > m + 8.f)) {
;         const float mn = fmaxf(m, mx);
;         const float alpha = __builtin_amdgcn_exp2f(m - mn);
;         m = mn; l *= alpha;
; #pragma unroll
;         for (int dt = 0; dt < 4; ++dt)
; #pragma unroll
;             for (int i = 0; i < 16; ++i) O[dt][i] *= alpha;
;     }
; DI void attn_prompt_item(const __attribute__((address_space(4))) Args& a, LAS unsigned char* lds, int ws_, int b, int h, int qt, float lam, bool dry = false) {
;     ...
;     for (int kt = 0; kt < nt; ++kt) {
;         const bool more = kt + 1 < nt;
;         if (more) {
; #pragma unroll
;             for (int i = 0; i < 2; ++i) { kx[i] = *(const v4u*)(ksrc[i] + (size_t)(kt + 1) * 64 * 1024); vx[i] = *(const v4u*)(vsrc[i] + (kt + 1) * 64); }
;         }
;         const LAS unsigned char* buf = lds + (kt & 1) * KV_BYTES;
;         if (kt < my_nt) attn_tile<2>(buf, buf + KT_BYTES, map, lane, Q, O, m, l);
;         if (more) {
;             LAS unsigned char* nb = lds + ((kt + 1) & 1) * KV_BYTES;
; #pragma unroll
;             for (int i = 0; i < 2; ++i) { *(LAS v4u*)(nb + kdst[i]) = kx[i]; *(LAS v4u*)(nb + vdst[i]) = vx[i]; }
;         }
;         __syncthreads();
.LBB0_1432:
	s_add_i32 s9, s9, 1
	s_bitcmp1_b32 s9, 0
	s_cselect_b32 s10, 0x8c00, 0
	s_add_i32 s10, s10, 0
	v_add_u32_e32 v64, s10, v132
	s_waitcnt vmcnt(3)
	ds_write_b128 v64, v[118:121]
	v_add_u32_e32 v64, s10, v134
	s_waitcnt vmcnt(2)
	ds_write_b128 v64, v[114:117] offset:17408
	v_add_u32_e32 v64, s10, v136
	s_waitcnt vmcnt(1)
	ds_write_b128 v64, v[126:129]
	v_add_u32_e32 v64, s10, v138
	v_lshl_add_u64 v[140:141], v[140:141], 0, s[28:29]
	v_lshl_add_u64 v[142:143], v[142:143], 0, s[28:29]
	v_lshl_add_u64 v[144:145], v[144:145], 0, s[30:31]
	s_cmp_eq_u32 s8, s9
	v_lshl_add_u64 v[146:147], v[146:147], 0, s[30:31]
	s_waitcnt vmcnt(0)
	ds_write_b128 v64, v[122:125] offset:17408
	s_cbranch_scc1 .Lnold_b
	v_lshl_add_u64 v[64:65], s[36:37], 0, v[146:147]
	v_lshl_add_u64 v[66:67], s[36:37], 0, v[142:143]
	global_load_dwordx4 v[118:121], v[64:65], off
	global_load_dwordx4 v[114:117], v[66:67], off
	v_lshl_add_u64 v[64:65], s[36:37], 0, v[144:145]
	v_lshl_add_u64 v[66:67], s[36:37], 0, v[140:141]
	global_load_dwordx4 v[126:129], v[64:65], off
	global_load_dwordx4 v[122:125], v[66:67], off
.Lnold_b:
	s_waitcnt lgkmcnt(0)
	s_barrier
	s_cbranch_scc1 .LBB0_1436
.LBB0_1433:
	s_cmp_ge_u32 s9, s7
	s_cbranch_scc1 .LBB0_1432
	s_bitcmp1_b32 s9, 0
	s_cselect_b32 s10, 0x8c00, 0
	s_add_i32 s10, s10, 0
	s_setprio 1
	s_add_i32 s11, s10, s89
	v_add_u32_e32 v72, s11, v130
	v_add_u32_e32 v73, v72, v153
	v_add_u32_e32 v155, v72, v154
	ds_read_b128 v[64:67], v73
	ds_read_b128 v[68:71], v73 offset:32
	ds_read_b128 v[232:235], v73 offset:64
	ds_read_b128 v[236:239], v73 offset:96
	ds_read_b128 v[240:243], v155
	ds_read_b128 v[244:247], v155 offset:32
	ds_read_b128 v[248:251], v155 offset:64
	ds_read_b128 v[156:159], v155 offset:96
	s_waitcnt vmcnt(7) lgkmcnt(7)
	v_mfma_f32_32x32x16_bf16 v[80:95], v[64:67], v[110:113], v[192:207]
	s_waitcnt vmcnt(6) lgkmcnt(6)
	v_mfma_f32_32x32x16_bf16 v[80:95], v[68:71], v[106:109], v[80:95]
	s_waitcnt vmcnt(5) lgkmcnt(5)
	v_mfma_f32_32x32x16_bf16 v[80:95], v[232:235], v[102:105], v[80:95]
	s_waitcnt vmcnt(4) lgkmcnt(4)
	v_mfma_f32_32x32x16_bf16 v[80:95], v[236:239], v[98:101], v[80:95]
	s_waitcnt lgkmcnt(3)
	v_mfma_f32_32x32x16_bf16 v[64:79], v[240:243], v[110:113], v[192:207]
	s_waitcnt lgkmcnt(2)
	v_mfma_f32_32x32x16_bf16 v[64:79], v[244:247], v[106:109], v[64:79]
	s_waitcnt lgkmcnt(1)
	v_mfma_f32_32x32x16_bf16 v[64:79], v[248:251], v[102:105], v[64:79]
	s_waitcnt lgkmcnt(0)
	v_mfma_f32_32x32x16_bf16 v[64:79], v[156:159], v[98:101], v[64:79]
	s_setprio 0
	s_nop 0
	v_max_f32_e32 v155, v81, v81
	v_max_f32_e32 v156, v80, v80
	v_max_f32_e32 v155, v156, v155
	v_max3_f32 v155, v155, v82, v83
	v_max3_f32 v155, v155, v84, v85
	v_max3_f32 v155, v155, v86, v87
	v_max3_f32 v155, v155, v88, v89
	v_max3_f32 v155, v155, v90, v91
	v_max3_f32 v155, v155, v92, v93
	v_max3_f32 v155, v155, v94, v95
	v_max3_f32 v155, v155, v64, v65
	v_max3_f32 v155, v155, v66, v67
	v_max3_f32 v155, v155, v68, v69
	v_max3_f32 v155, v155, v70, v71
	v_max3_f32 v155, v155, v72, v73
	v_max3_f32 v155, v155, v74, v75
	v_max3_f32 v155, v155, v76, v77
	v_max3_f32 v155, v155, v78, v79
	v_mov_b32_e32 v156, v155
	s_nop 1
	v_permlane32_swap_b32_e32 v155, v156
	v_max_f32_e32 v156, v156, v156
	v_max_f32_e32 v155, v155, v155
	v_max_f32_e32 v155, v155, v156
	v_cmp_gt_f32_e32 vcc, v155, v152
	s_cbranch_vccz .LBB0_1431
	v_max_f32_e32 v155, v155, v209
	v_max_f32_e32 v156, 0, v155
	v_mul_f32_e32 v156, -1.0, v156
	v_exp_f32_e32 v156, v156
	v_sub_f32_e32 v192, v192, v155
	v_mov_b32_e32 v152, 0x41000000
	v_mov_b32_e32 v209, 0
	v_sub_f32_e32 v80, v80, v155
	v_sub_f32_e32 v81, v81, v155
	v_sub_f32_e32 v82, v82, v155
	v_sub_f32_e32 v83, v83, v155
	v_sub_f32_e32 v84, v84, v155
	v_sub_f32_e32 v85, v85, v155
	v_sub_f32_e32 v86, v86, v155
	v_sub_f32_e32 v87, v87, v155
	v_sub_f32_e32 v88, v88, v155
	v_sub_f32_e32 v89, v89, v155
	v_sub_f32_e32 v90, v90, v155
	v_sub_f32_e32 v91, v91, v155
	v_sub_f32_e32 v92, v92, v155
	v_sub_f32_e32 v93, v93, v155
	v_sub_f32_e32 v94, v94, v155
	v_sub_f32_e32 v95, v95, v155
	v_sub_f32_e32 v64, v64, v155
	v_sub_f32_e32 v65, v65, v155
	v_sub_f32_e32 v66, v66, v155
	v_sub_f32_e32 v67, v67, v155
	v_sub_f32_e32 v68, v68, v155
	v_sub_f32_e32 v69, v69, v155
	v_sub_f32_e32 v70, v70, v155
	v_sub_f32_e32 v71, v71, v155
	v_sub_f32_e32 v72, v72, v155
	v_sub_f32_e32 v73, v73, v155
	v_sub_f32_e32 v74, v74, v155
	v_sub_f32_e32 v75, v75, v155
	v_sub_f32_e32 v76, v76, v155
	v_sub_f32_e32 v77, v77, v155
	v_sub_f32_e32 v78, v78, v155
	v_sub_f32_e32 v79, v79, v155
	v_mov_b32_e32 v193, v192
	v_mov_b32_e32 v194, v192
	v_mov_b32_e32 v195, v192
	v_mov_b32_e32 v196, v192
	v_mov_b32_e32 v197, v192
	v_mov_b32_e32 v198, v192
	v_mov_b32_e32 v199, v192
	v_mov_b32_e32 v200, v192
	v_mov_b32_e32 v201, v192
	v_mov_b32_e32 v202, v192
	v_mov_b32_e32 v203, v192
	v_mov_b32_e32 v204, v192
	v_mov_b32_e32 v205, v192
	v_mov_b32_e32 v206, v192
	v_mov_b32_e32 v207, v192
	v_mul_f32_e32 v133, v133, v156
	v_pk_mul_f32 v[62:63], v[62:63], v[156:157] op_sel_hi:[1,0]
	v_pk_mul_f32 v[60:61], v[60:61], v[156:157] op_sel_hi:[1,0]
	v_pk_mul_f32 v[58:59], v[58:59], v[156:157] op_sel_hi:[1,0]
	v_pk_mul_f32 v[56:57], v[56:57], v[156:157] op_sel_hi:[1,0]
	v_pk_mul_f32 v[54:55], v[54:55], v[156:157] op_sel_hi:[1,0]
	v_pk_mul_f32 v[52:53], v[52:53], v[156:157] op_sel_hi:[1,0]
	v_pk_mul_f32 v[50:51], v[50:51], v[156:157] op_sel_hi:[1,0]
	v_pk_mul_f32 v[48:49], v[48:49], v[156:157] op_sel_hi:[1,0]
	v_pk_mul_f32 v[46:47], v[46:47], v[156:157] op_sel_hi:[1,0]
	v_pk_mul_f32 v[44:45], v[44:45], v[156:157] op_sel_hi:[1,0]
	v_pk_mul_f32 v[42:43], v[42:43], v[156:157] op_sel_hi:[1,0]
	v_pk_mul_f32 v[40:41], v[40:41], v[156:157] op_sel_hi:[1,0]
	v_pk_mul_f32 v[38:39], v[38:39], v[156:157] op_sel_hi:[1,0]
	v_pk_mul_f32 v[36:37], v[36:37], v[156:157] op_sel_hi:[1,0]
	v_pk_mul_f32 v[34:35], v[34:35], v[156:157] op_sel_hi:[1,0]
	v_pk_mul_f32 v[32:33], v[32:33], v[156:157] op_sel_hi:[1,0]
	v_pk_mul_f32 v[30:31], v[30:31], v[156:157] op_sel_hi:[1,0]
	v_pk_mul_f32 v[28:29], v[28:29], v[156:157] op_sel_hi:[1,0]
	v_pk_mul_f32 v[26:27], v[26:27], v[156:157] op_sel_hi:[1,0]
	v_pk_mul_f32 v[24:25], v[24:25], v[156:157] op_sel_hi:[1,0]
	v_pk_mul_f32 v[22:23], v[22:23], v[156:157] op_sel_hi:[1,0]
	v_pk_mul_f32 v[20:21], v[20:21], v[156:157] op_sel_hi:[1,0]
	v_pk_mul_f32 v[18:19], v[18:19], v[156:157] op_sel_hi:[1,0]
	v_pk_mul_f32 v[16:17], v[16:17], v[156:157] op_sel_hi:[1,0]
	v_pk_mul_f32 v[14:15], v[14:15], v[156:157] op_sel_hi:[1,0]
	v_pk_mul_f32 v[12:13], v[12:13], v[156:157] op_sel_hi:[1,0]
	v_pk_mul_f32 v[10:11], v[10:11], v[156:157] op_sel_hi:[1,0]
	v_pk_mul_f32 v[8:9], v[8:9], v[156:157] op_sel_hi:[1,0]
	v_pk_mul_f32 v[6:7], v[6:7], v[156:157] op_sel_hi:[1,0]
	v_pk_mul_f32 v[4:5], v[4:5], v[156:157] op_sel_hi:[1,0]
	v_pk_mul_f32 v[2:3], v[2:3], v[156:157] op_sel_hi:[1,0]
	v_pk_mul_f32 v[0:1], v[0:1], v[156:157] op_sel_hi:[1,0]
	s_branch .LBB0_1431
